# GEMM K-loops: uniform DMA spread, 1 DMA per 4 MFMAs over the whole K-step (2 A-tile DMAs after the landing barrier)
# baseline (speedup 1.0000x reference)
.Lodwin_loop:
	ds_read_b128 v[148:151], v138 offset:0
	ds_read_b128 v[172:175], v139 offset:16384
	ds_read_b128 v[176:179], v139 offset:18432
	ds_read_b128 v[152:155], v138 offset:2048
	ds_read_b128 v[180:183], v139 offset:20480
	ds_read_b128 v[184:187], v139 offset:22528
	ds_read_b128 v[156:159], v138 offset:4096
	ds_read_b128 v[168:171], v138 offset:6144
	s_waitcnt lgkmcnt(8)
	s_add_u32 m0, s64, 0xc000
	v_mfma_f32_16x16x32_bf16 v[62:65], v[66:69], v[82:85], v[62:65]
	v_mfma_f32_16x16x32_bf16 v[58:61], v[66:69], v[86:89], v[58:61]
	global_load_lds_dwordx4 v144, s[62:63]
	v_mfma_f32_16x16x32_bf16 v[54:57], v[66:69], v[90:93], v[54:57]
	v_mfma_f32_16x16x32_bf16 v[50:53], v[66:69], v[94:97], v[50:53]
	s_add_u32 m0, s64, 0xd000
	v_mfma_f32_16x16x32_bf16 v[46:49], v[70:73], v[82:85], v[46:49]
	v_mfma_f32_16x16x32_bf16 v[42:45], v[70:73], v[86:89], v[42:45]
	global_load_lds_dwordx4 v145, s[62:63]
	v_mfma_f32_16x16x32_bf16 v[34:37], v[70:73], v[90:93], v[34:37]
	v_mfma_f32_16x16x32_bf16 v[30:33], v[70:73], v[94:97], v[30:33]
	s_add_u32 m0, s64, 0xe000
	v_mfma_f32_16x16x32_bf16 v[26:29], v[74:77], v[82:85], v[26:29]
	v_mfma_f32_16x16x32_bf16 v[22:25], v[74:77], v[86:89], v[22:25]
	global_load_lds_dwordx4 v146, s[62:63]
	v_mfma_f32_16x16x32_bf16 v[18:21], v[74:77], v[90:93], v[18:21]
	v_mfma_f32_16x16x32_bf16 v[14:17], v[74:77], v[94:97], v[14:17]
	s_add_u32 m0, s64, 0xf000
	v_mfma_f32_16x16x32_bf16 v[10:13], v[78:81], v[82:85], v[10:13]
	v_mfma_f32_16x16x32_bf16 v[6:9], v[78:81], v[86:89], v[6:9]
	global_load_lds_dwordx4 v147, s[62:63]
	v_mfma_f32_16x16x32_bf16 v[2:5], v[78:81], v[90:93], v[2:5]
	v_mfma_f32_16x16x32_bf16 v[38:41], v[78:81], v[94:97], v[38:41]
	s_add_u32 s62, s62, 0x80
	s_addc_u32 s63, s63, 0
	s_waitcnt lgkmcnt(0)
	s_barrier
	s_add_u32 m0, s64, 0x0
	v_mfma_f32_16x16x32_bf16 v[62:65], v[148:151], v[172:175], v[62:65]
	v_mfma_f32_16x16x32_bf16 v[58:61], v[148:151], v[176:179], v[58:61]
	global_load_lds_dwordx4 v140, s[60:61]
	v_mfma_f32_16x16x32_bf16 v[54:57], v[148:151], v[180:183], v[54:57]
	v_mfma_f32_16x16x32_bf16 v[50:53], v[148:151], v[184:187], v[50:53]
	s_add_u32 m0, s64, 0x1000
	v_mfma_f32_16x16x32_bf16 v[46:49], v[152:155], v[172:175], v[46:49]
	v_mfma_f32_16x16x32_bf16 v[42:45], v[152:155], v[176:179], v[42:45]
	global_load_lds_dwordx4 v141, s[60:61]
	v_mfma_f32_16x16x32_bf16 v[34:37], v[152:155], v[180:183], v[34:37]
	v_mfma_f32_16x16x32_bf16 v[30:33], v[152:155], v[184:187], v[30:33]
	s_waitcnt vmcnt(2)
	s_barrier
	ds_read_b128 v[66:69], v136 offset:32768
	ds_read_b128 v[82:85], v137 offset:49152
	ds_read_b128 v[86:89], v137 offset:51200
	ds_read_b128 v[70:73], v136 offset:34816
	ds_read_b128 v[90:93], v137 offset:53248
	ds_read_b128 v[94:97], v137 offset:55296
	ds_read_b128 v[74:77], v136 offset:36864
	ds_read_b128 v[78:81], v136 offset:38912
	s_add_u32 m0, s64, 0x2000
	v_mfma_f32_16x16x32_bf16 v[26:29], v[156:159], v[172:175], v[26:29]
	v_mfma_f32_16x16x32_bf16 v[22:25], v[156:159], v[176:179], v[22:25]
	global_load_lds_dwordx4 v142, s[60:61]
	v_mfma_f32_16x16x32_bf16 v[18:21], v[156:159], v[180:183], v[18:21]
	v_mfma_f32_16x16x32_bf16 v[14:17], v[156:159], v[184:187], v[14:17]
	s_add_u32 m0, s64, 0x3000
	v_mfma_f32_16x16x32_bf16 v[10:13], v[168:171], v[172:175], v[10:13]
	v_mfma_f32_16x16x32_bf16 v[6:9], v[168:171], v[176:179], v[6:9]
	global_load_lds_dwordx4 v143, s[60:61]
	v_mfma_f32_16x16x32_bf16 v[2:5], v[168:171], v[180:183], v[2:5]
	v_mfma_f32_16x16x32_bf16 v[38:41], v[168:171], v[184:187], v[38:41]
	s_add_u32 s60, s60, 0x80
	s_addc_u32 s61, s61, 0
	ds_read_b128 v[148:151], v138 offset:32768
	ds_read_b128 v[172:175], v139 offset:49152
	ds_read_b128 v[176:179], v139 offset:51200
	ds_read_b128 v[152:155], v138 offset:34816
	ds_read_b128 v[180:183], v139 offset:53248
	ds_read_b128 v[184:187], v139 offset:55296
	ds_read_b128 v[156:159], v138 offset:36864
	ds_read_b128 v[168:171], v138 offset:38912
	s_waitcnt lgkmcnt(8)
	s_add_u32 m0, s64, 0x4000
	v_mfma_f32_16x16x32_bf16 v[62:65], v[66:69], v[82:85], v[62:65]
	v_mfma_f32_16x16x32_bf16 v[58:61], v[66:69], v[86:89], v[58:61]
	global_load_lds_dwordx4 v144, s[62:63]
	v_mfma_f32_16x16x32_bf16 v[54:57], v[66:69], v[90:93], v[54:57]
	v_mfma_f32_16x16x32_bf16 v[50:53], v[66:69], v[94:97], v[50:53]
	s_add_u32 m0, s64, 0x5000
	v_mfma_f32_16x16x32_bf16 v[46:49], v[70:73], v[82:85], v[46:49]
	v_mfma_f32_16x16x32_bf16 v[42:45], v[70:73], v[86:89], v[42:45]
	global_load_lds_dwordx4 v145, s[62:63]
	v_mfma_f32_16x16x32_bf16 v[34:37], v[70:73], v[90:93], v[34:37]
	v_mfma_f32_16x16x32_bf16 v[30:33], v[70:73], v[94:97], v[30:33]
	s_add_u32 m0, s64, 0x6000
	v_mfma_f32_16x16x32_bf16 v[26:29], v[74:77], v[82:85], v[26:29]
	v_mfma_f32_16x16x32_bf16 v[22:25], v[74:77], v[86:89], v[22:25]
	global_load_lds_dwordx4 v146, s[62:63]
	v_mfma_f32_16x16x32_bf16 v[18:21], v[74:77], v[90:93], v[18:21]
	v_mfma_f32_16x16x32_bf16 v[14:17], v[74:77], v[94:97], v[14:17]
	s_add_u32 m0, s64, 0x7000
	v_mfma_f32_16x16x32_bf16 v[10:13], v[78:81], v[82:85], v[10:13]
	v_mfma_f32_16x16x32_bf16 v[6:9], v[78:81], v[86:89], v[6:9]
	global_load_lds_dwordx4 v147, s[62:63]
	v_mfma_f32_16x16x32_bf16 v[2:5], v[78:81], v[90:93], v[2:5]
	v_mfma_f32_16x16x32_bf16 v[38:41], v[78:81], v[94:97], v[38:41]
	s_add_u32 s62, s62, 0x80
	s_addc_u32 s63, s63, 0
	s_waitcnt lgkmcnt(0)
	s_barrier
	s_add_u32 m0, s64, 0x8000
	v_mfma_f32_16x16x32_bf16 v[62:65], v[148:151], v[172:175], v[62:65]
	v_mfma_f32_16x16x32_bf16 v[58:61], v[148:151], v[176:179], v[58:61]
	global_load_lds_dwordx4 v140, s[60:61]
	v_mfma_f32_16x16x32_bf16 v[54:57], v[148:151], v[180:183], v[54:57]
	v_mfma_f32_16x16x32_bf16 v[50:53], v[148:151], v[184:187], v[50:53]
	s_add_u32 m0, s64, 0x9000
	v_mfma_f32_16x16x32_bf16 v[46:49], v[152:155], v[172:175], v[46:49]
	v_mfma_f32_16x16x32_bf16 v[42:45], v[152:155], v[176:179], v[42:45]
	global_load_lds_dwordx4 v141, s[60:61]
	v_mfma_f32_16x16x32_bf16 v[34:37], v[152:155], v[180:183], v[34:37]
	v_mfma_f32_16x16x32_bf16 v[30:33], v[152:155], v[184:187], v[30:33]
	s_waitcnt vmcnt(2)
	s_barrier
	ds_read_b128 v[66:69], v136 offset:0
	ds_read_b128 v[82:85], v137 offset:16384
	ds_read_b128 v[86:89], v137 offset:18432
	ds_read_b128 v[70:73], v136 offset:2048
	ds_read_b128 v[90:93], v137 offset:20480
	ds_read_b128 v[94:97], v137 offset:22528
	ds_read_b128 v[74:77], v136 offset:4096
	ds_read_b128 v[78:81], v136 offset:6144
	s_add_u32 m0, s64, 0xa000
	v_mfma_f32_16x16x32_bf16 v[26:29], v[156:159], v[172:175], v[26:29]
	v_mfma_f32_16x16x32_bf16 v[22:25], v[156:159], v[176:179], v[22:25]
	global_load_lds_dwordx4 v142, s[60:61]
	v_mfma_f32_16x16x32_bf16 v[18:21], v[156:159], v[180:183], v[18:21]
	v_mfma_f32_16x16x32_bf16 v[14:17], v[156:159], v[184:187], v[14:17]
	s_add_u32 m0, s64, 0xb000
	v_mfma_f32_16x16x32_bf16 v[10:13], v[168:171], v[172:175], v[10:13]
	v_mfma_f32_16x16x32_bf16 v[6:9], v[168:171], v[176:179], v[6:9]
	global_load_lds_dwordx4 v143, s[60:61]
	v_mfma_f32_16x16x32_bf16 v[2:5], v[168:171], v[180:183], v[2:5]
	v_mfma_f32_16x16x32_bf16 v[38:41], v[168:171], v[184:187], v[38:41]
	s_add_u32 s60, s60, 0x80
	s_addc_u32 s61, s61, 0
	s_sub_i32 s65, s65, 1
	s_cmp_lg_u32 s65, 0
	s_cbranch_scc1 .Lodwin_loop
	ds_read_b128 v[148:151], v138 offset:0
	ds_read_b128 v[172:175], v139 offset:16384
	ds_read_b128 v[176:179], v139 offset:18432
	ds_read_b128 v[152:155], v138 offset:2048
	ds_read_b128 v[180:183], v139 offset:20480
	ds_read_b128 v[184:187], v139 offset:22528
	ds_read_b128 v[156:159], v138 offset:4096
	ds_read_b128 v[168:171], v138 offset:6144
	s_waitcnt lgkmcnt(8)
	s_add_u32 m0, s64, 0xc000
	v_mfma_f32_16x16x32_bf16 v[62:65], v[66:69], v[82:85], v[62:65]
	v_mfma_f32_16x16x32_bf16 v[58:61], v[66:69], v[86:89], v[58:61]
	global_load_lds_dwordx4 v144, s[62:63]
	v_mfma_f32_16x16x32_bf16 v[54:57], v[66:69], v[90:93], v[54:57]
	v_mfma_f32_16x16x32_bf16 v[50:53], v[66:69], v[94:97], v[50:53]
	s_add_u32 m0, s64, 0xd000
	v_mfma_f32_16x16x32_bf16 v[46:49], v[70:73], v[82:85], v[46:49]
	v_mfma_f32_16x16x32_bf16 v[42:45], v[70:73], v[86:89], v[42:45]
	global_load_lds_dwordx4 v145, s[62:63]
	v_mfma_f32_16x16x32_bf16 v[34:37], v[70:73], v[90:93], v[34:37]
	v_mfma_f32_16x16x32_bf16 v[30:33], v[70:73], v[94:97], v[30:33]
	s_add_u32 m0, s64, 0xe000
	v_mfma_f32_16x16x32_bf16 v[26:29], v[74:77], v[82:85], v[26:29]
	v_mfma_f32_16x16x32_bf16 v[22:25], v[74:77], v[86:89], v[22:25]
	global_load_lds_dwordx4 v146, s[62:63]
	v_mfma_f32_16x16x32_bf16 v[18:21], v[74:77], v[90:93], v[18:21]
	v_mfma_f32_16x16x32_bf16 v[14:17], v[74:77], v[94:97], v[14:17]
	s_add_u32 m0, s64, 0xf000
	v_mfma_f32_16x16x32_bf16 v[10:13], v[78:81], v[82:85], v[10:13]
	v_mfma_f32_16x16x32_bf16 v[6:9], v[78:81], v[86:89], v[6:9]
	global_load_lds_dwordx4 v147, s[62:63]
	v_mfma_f32_16x16x32_bf16 v[2:5], v[78:81], v[90:93], v[2:5]
	v_mfma_f32_16x16x32_bf16 v[38:41], v[78:81], v[94:97], v[38:41]
	s_add_u32 s62, s62, 0x80
	s_addc_u32 s63, s63, 0
	s_waitcnt lgkmcnt(0)
	s_barrier
	v_mfma_f32_16x16x32_bf16 v[62:65], v[148:151], v[172:175], v[62:65]
	v_mfma_f32_16x16x32_bf16 v[58:61], v[148:151], v[176:179], v[58:61]
	v_mfma_f32_16x16x32_bf16 v[54:57], v[148:151], v[180:183], v[54:57]
	v_mfma_f32_16x16x32_bf16 v[50:53], v[148:151], v[184:187], v[50:53]
	v_mfma_f32_16x16x32_bf16 v[46:49], v[152:155], v[172:175], v[46:49]
	v_mfma_f32_16x16x32_bf16 v[42:45], v[152:155], v[176:179], v[42:45]
	v_mfma_f32_16x16x32_bf16 v[34:37], v[152:155], v[180:183], v[34:37]
	v_mfma_f32_16x16x32_bf16 v[30:33], v[152:155], v[184:187], v[30:33]
	s_waitcnt vmcnt(0)
	s_barrier
	ds_read_b128 v[66:69], v136 offset:32768
	ds_read_b128 v[82:85], v137 offset:49152
	ds_read_b128 v[86:89], v137 offset:51200
	ds_read_b128 v[70:73], v136 offset:34816
	ds_read_b128 v[90:93], v137 offset:53248
	ds_read_b128 v[94:97], v137 offset:55296
	ds_read_b128 v[74:77], v136 offset:36864
	ds_read_b128 v[78:81], v136 offset:38912
	v_mfma_f32_16x16x32_bf16 v[26:29], v[156:159], v[172:175], v[26:29]
	v_mfma_f32_16x16x32_bf16 v[22:25], v[156:159], v[176:179], v[22:25]
	v_mfma_f32_16x16x32_bf16 v[18:21], v[156:159], v[180:183], v[18:21]
	v_mfma_f32_16x16x32_bf16 v[14:17], v[156:159], v[184:187], v[14:17]
	v_mfma_f32_16x16x32_bf16 v[10:13], v[168:171], v[172:175], v[10:13]
	v_mfma_f32_16x16x32_bf16 v[6:9], v[168:171], v[176:179], v[6:9]
	v_mfma_f32_16x16x32_bf16 v[2:5], v[168:171], v[180:183], v[2:5]
	v_mfma_f32_16x16x32_bf16 v[38:41], v[168:171], v[184:187], v[38:41]
	ds_read_b128 v[148:151], v138 offset:32768
	ds_read_b128 v[172:175], v139 offset:49152
	ds_read_b128 v[176:179], v139 offset:51200
	ds_read_b128 v[152:155], v138 offset:34816
	ds_read_b128 v[180:183], v139 offset:53248
	ds_read_b128 v[184:187], v139 offset:55296
	ds_read_b128 v[156:159], v138 offset:36864
	ds_read_b128 v[168:171], v138 offset:38912
	s_waitcnt lgkmcnt(8)
	v_mfma_f32_16x16x32_bf16 v[62:65], v[66:69], v[82:85], v[62:65]
	v_mfma_f32_16x16x32_bf16 v[58:61], v[66:69], v[86:89], v[58:61]
	v_mfma_f32_16x16x32_bf16 v[54:57], v[66:69], v[90:93], v[54:57]
	v_mfma_f32_16x16x32_bf16 v[50:53], v[66:69], v[94:97], v[50:53]
	v_mfma_f32_16x16x32_bf16 v[46:49], v[70:73], v[82:85], v[46:49]
	v_mfma_f32_16x16x32_bf16 v[42:45], v[70:73], v[86:89], v[42:45]
	v_mfma_f32_16x16x32_bf16 v[34:37], v[70:73], v[90:93], v[34:37]
	v_mfma_f32_16x16x32_bf16 v[30:33], v[70:73], v[94:97], v[30:33]
	v_mfma_f32_16x16x32_bf16 v[26:29], v[74:77], v[82:85], v[26:29]
	v_mfma_f32_16x16x32_bf16 v[22:25], v[74:77], v[86:89], v[22:25]
	v_mfma_f32_16x16x32_bf16 v[18:21], v[74:77], v[90:93], v[18:21]
	v_mfma_f32_16x16x32_bf16 v[14:17], v[74:77], v[94:97], v[14:17]
	v_mfma_f32_16x16x32_bf16 v[10:13], v[78:81], v[82:85], v[10:13]
	v_mfma_f32_16x16x32_bf16 v[6:9], v[78:81], v[86:89], v[6:9]
	v_mfma_f32_16x16x32_bf16 v[2:5], v[78:81], v[90:93], v[2:5]
	v_mfma_f32_16x16x32_bf16 v[38:41], v[78:81], v[94:97], v[38:41]
	s_waitcnt lgkmcnt(0)
	s_barrier
	v_mfma_f32_16x16x32_bf16 v[62:65], v[148:151], v[172:175], v[62:65]
	v_mfma_f32_16x16x32_bf16 v[58:61], v[148:151], v[176:179], v[58:61]
	v_mfma_f32_16x16x32_bf16 v[54:57], v[148:151], v[180:183], v[54:57]
	v_mfma_f32_16x16x32_bf16 v[50:53], v[148:151], v[184:187], v[50:53]
	v_mfma_f32_16x16x32_bf16 v[46:49], v[152:155], v[172:175], v[46:49]
	v_mfma_f32_16x16x32_bf16 v[42:45], v[152:155], v[176:179], v[42:45]
	v_mfma_f32_16x16x32_bf16 v[34:37], v[152:155], v[180:183], v[34:37]
	v_mfma_f32_16x16x32_bf16 v[30:33], v[152:155], v[184:187], v[30:33]
	v_mfma_f32_16x16x32_bf16 v[26:29], v[156:159], v[172:175], v[26:29]
	v_mfma_f32_16x16x32_bf16 v[22:25], v[156:159], v[176:179], v[22:25]
	v_mfma_f32_16x16x32_bf16 v[18:21], v[156:159], v[180:183], v[18:21]
	v_mfma_f32_16x16x32_bf16 v[14:17], v[156:159], v[184:187], v[14:17]
	v_mfma_f32_16x16x32_bf16 v[10:13], v[168:171], v[172:175], v[10:13]
	v_mfma_f32_16x16x32_bf16 v[6:9], v[168:171], v[176:179], v[6:9]
	v_mfma_f32_16x16x32_bf16 v[2:5], v[168:171], v[180:183], v[2:5]
	v_mfma_f32_16x16x32_bf16 v[38:41], v[168:171], v[184:187], v[38:41]

.Levwin_loop:
	ds_read_b128 v[148:151], v138 offset:0
	ds_read_b128 v[172:175], v139 offset:16384
	ds_read_b128 v[176:179], v139 offset:18432
	ds_read_b128 v[152:155], v138 offset:2048
	ds_read_b128 v[180:183], v139 offset:20480
	ds_read_b128 v[184:187], v139 offset:22528
	ds_read_b128 v[156:159], v138 offset:4096
	ds_read_b128 v[168:171], v138 offset:6144
	s_waitcnt lgkmcnt(8)
	s_add_u32 m0, s64, 0xc000
	v_mfma_f32_16x16x32_bf16 v[62:65], v[66:69], v[82:85], v[62:65]
	v_mfma_f32_16x16x32_bf16 v[58:61], v[66:69], v[86:89], v[58:61]
	global_load_lds_dwordx4 v144, s[62:63]
	v_mfma_f32_16x16x32_bf16 v[54:57], v[66:69], v[90:93], v[54:57]
	v_mfma_f32_16x16x32_bf16 v[50:53], v[66:69], v[94:97], v[50:53]
	s_add_u32 m0, s64, 0xd000
	v_mfma_f32_16x16x32_bf16 v[46:49], v[70:73], v[82:85], v[46:49]
	v_mfma_f32_16x16x32_bf16 v[38:41], v[70:73], v[86:89], v[38:41]
	global_load_lds_dwordx4 v145, s[62:63]
	v_mfma_f32_16x16x32_bf16 v[34:37], v[70:73], v[90:93], v[34:37]
	v_mfma_f32_16x16x32_bf16 v[30:33], v[70:73], v[94:97], v[30:33]
	s_add_u32 m0, s64, 0xe000
	v_mfma_f32_16x16x32_bf16 v[26:29], v[74:77], v[82:85], v[26:29]
	v_mfma_f32_16x16x32_bf16 v[22:25], v[74:77], v[86:89], v[22:25]
	global_load_lds_dwordx4 v146, s[62:63]
	v_mfma_f32_16x16x32_bf16 v[18:21], v[74:77], v[90:93], v[18:21]
	v_mfma_f32_16x16x32_bf16 v[14:17], v[74:77], v[94:97], v[14:17]
	s_add_u32 m0, s64, 0xf000
	v_mfma_f32_16x16x32_bf16 v[10:13], v[78:81], v[82:85], v[10:13]
	v_mfma_f32_16x16x32_bf16 v[6:9], v[78:81], v[86:89], v[6:9]
	global_load_lds_dwordx4 v147, s[62:63]
	v_mfma_f32_16x16x32_bf16 v[2:5], v[78:81], v[90:93], v[2:5]
	v_mfma_f32_16x16x32_bf16 v[42:45], v[78:81], v[94:97], v[42:45]
	s_add_u32 s62, s62, 0x80
	s_addc_u32 s63, s63, 0
	s_waitcnt lgkmcnt(0)
	s_barrier
	s_add_u32 m0, s64, 0x0
	v_mfma_f32_16x16x32_bf16 v[62:65], v[148:151], v[172:175], v[62:65]
	v_mfma_f32_16x16x32_bf16 v[58:61], v[148:151], v[176:179], v[58:61]
	global_load_lds_dwordx4 v140, s[60:61]
	v_mfma_f32_16x16x32_bf16 v[54:57], v[148:151], v[180:183], v[54:57]
	v_mfma_f32_16x16x32_bf16 v[50:53], v[148:151], v[184:187], v[50:53]
	s_add_u32 m0, s64, 0x1000
	v_mfma_f32_16x16x32_bf16 v[46:49], v[152:155], v[172:175], v[46:49]
	v_mfma_f32_16x16x32_bf16 v[38:41], v[152:155], v[176:179], v[38:41]
	global_load_lds_dwordx4 v141, s[60:61]
	v_mfma_f32_16x16x32_bf16 v[34:37], v[152:155], v[180:183], v[34:37]
	v_mfma_f32_16x16x32_bf16 v[30:33], v[152:155], v[184:187], v[30:33]
	s_waitcnt vmcnt(2)
	s_barrier
	ds_read_b128 v[66:69], v136 offset:32768
	ds_read_b128 v[82:85], v137 offset:49152
	ds_read_b128 v[86:89], v137 offset:51200
	ds_read_b128 v[70:73], v136 offset:34816
	ds_read_b128 v[90:93], v137 offset:53248
	ds_read_b128 v[94:97], v137 offset:55296
	ds_read_b128 v[74:77], v136 offset:36864
	ds_read_b128 v[78:81], v136 offset:38912
	s_add_u32 m0, s64, 0x2000
	v_mfma_f32_16x16x32_bf16 v[26:29], v[156:159], v[172:175], v[26:29]
	v_mfma_f32_16x16x32_bf16 v[22:25], v[156:159], v[176:179], v[22:25]
	global_load_lds_dwordx4 v142, s[60:61]
	v_mfma_f32_16x16x32_bf16 v[18:21], v[156:159], v[180:183], v[18:21]
	v_mfma_f32_16x16x32_bf16 v[14:17], v[156:159], v[184:187], v[14:17]
	s_add_u32 m0, s64, 0x3000
	v_mfma_f32_16x16x32_bf16 v[10:13], v[168:171], v[172:175], v[10:13]
	v_mfma_f32_16x16x32_bf16 v[6:9], v[168:171], v[176:179], v[6:9]
	global_load_lds_dwordx4 v143, s[60:61]
	v_mfma_f32_16x16x32_bf16 v[2:5], v[168:171], v[180:183], v[2:5]
	v_mfma_f32_16x16x32_bf16 v[42:45], v[168:171], v[184:187], v[42:45]
	s_add_u32 s60, s60, 0x80
	s_addc_u32 s61, s61, 0
	ds_read_b128 v[148:151], v138 offset:32768
	ds_read_b128 v[172:175], v139 offset:49152
	ds_read_b128 v[176:179], v139 offset:51200
	ds_read_b128 v[152:155], v138 offset:34816
	ds_read_b128 v[180:183], v139 offset:53248
	ds_read_b128 v[184:187], v139 offset:55296
	ds_read_b128 v[156:159], v138 offset:36864
	ds_read_b128 v[168:171], v138 offset:38912
	s_waitcnt lgkmcnt(8)
	s_add_u32 m0, s64, 0x4000
	v_mfma_f32_16x16x32_bf16 v[62:65], v[66:69], v[82:85], v[62:65]
	v_mfma_f32_16x16x32_bf16 v[58:61], v[66:69], v[86:89], v[58:61]
	global_load_lds_dwordx4 v144, s[62:63]
	v_mfma_f32_16x16x32_bf16 v[54:57], v[66:69], v[90:93], v[54:57]
	v_mfma_f32_16x16x32_bf16 v[50:53], v[66:69], v[94:97], v[50:53]
	s_add_u32 m0, s64, 0x5000
	v_mfma_f32_16x16x32_bf16 v[46:49], v[70:73], v[82:85], v[46:49]
	v_mfma_f32_16x16x32_bf16 v[38:41], v[70:73], v[86:89], v[38:41]
	global_load_lds_dwordx4 v145, s[62:63]
	v_mfma_f32_16x16x32_bf16 v[34:37], v[70:73], v[90:93], v[34:37]
	v_mfma_f32_16x16x32_bf16 v[30:33], v[70:73], v[94:97], v[30:33]
	s_add_u32 m0, s64, 0x6000
	v_mfma_f32_16x16x32_bf16 v[26:29], v[74:77], v[82:85], v[26:29]
	v_mfma_f32_16x16x32_bf16 v[22:25], v[74:77], v[86:89], v[22:25]
	global_load_lds_dwordx4 v146, s[62:63]
	v_mfma_f32_16x16x32_bf16 v[18:21], v[74:77], v[90:93], v[18:21]
	v_mfma_f32_16x16x32_bf16 v[14:17], v[74:77], v[94:97], v[14:17]
	s_add_u32 m0, s64, 0x7000
	v_mfma_f32_16x16x32_bf16 v[10:13], v[78:81], v[82:85], v[10:13]
	v_mfma_f32_16x16x32_bf16 v[6:9], v[78:81], v[86:89], v[6:9]
	global_load_lds_dwordx4 v147, s[62:63]
	v_mfma_f32_16x16x32_bf16 v[2:5], v[78:81], v[90:93], v[2:5]
	v_mfma_f32_16x16x32_bf16 v[42:45], v[78:81], v[94:97], v[42:45]
	s_add_u32 s62, s62, 0x80
	s_addc_u32 s63, s63, 0
	s_waitcnt lgkmcnt(0)
	s_barrier
	s_add_u32 m0, s64, 0x8000
	v_mfma_f32_16x16x32_bf16 v[62:65], v[148:151], v[172:175], v[62:65]
	v_mfma_f32_16x16x32_bf16 v[58:61], v[148:151], v[176:179], v[58:61]
	global_load_lds_dwordx4 v140, s[60:61]
	v_mfma_f32_16x16x32_bf16 v[54:57], v[148:151], v[180:183], v[54:57]
	v_mfma_f32_16x16x32_bf16 v[50:53], v[148:151], v[184:187], v[50:53]
	s_add_u32 m0, s64, 0x9000
	v_mfma_f32_16x16x32_bf16 v[46:49], v[152:155], v[172:175], v[46:49]
	v_mfma_f32_16x16x32_bf16 v[38:41], v[152:155], v[176:179], v[38:41]
	global_load_lds_dwordx4 v141, s[60:61]
	v_mfma_f32_16x16x32_bf16 v[34:37], v[152:155], v[180:183], v[34:37]
	v_mfma_f32_16x16x32_bf16 v[30:33], v[152:155], v[184:187], v[30:33]
	s_waitcnt vmcnt(2)
	s_barrier
	ds_read_b128 v[66:69], v136 offset:0
	ds_read_b128 v[82:85], v137 offset:16384
	ds_read_b128 v[86:89], v137 offset:18432
	ds_read_b128 v[70:73], v136 offset:2048
	ds_read_b128 v[90:93], v137 offset:20480
	ds_read_b128 v[94:97], v137 offset:22528
	ds_read_b128 v[74:77], v136 offset:4096
	ds_read_b128 v[78:81], v136 offset:6144
	s_add_u32 m0, s64, 0xa000
	v_mfma_f32_16x16x32_bf16 v[26:29], v[156:159], v[172:175], v[26:29]
	v_mfma_f32_16x16x32_bf16 v[22:25], v[156:159], v[176:179], v[22:25]
	global_load_lds_dwordx4 v142, s[60:61]
	v_mfma_f32_16x16x32_bf16 v[18:21], v[156:159], v[180:183], v[18:21]
	v_mfma_f32_16x16x32_bf16 v[14:17], v[156:159], v[184:187], v[14:17]
	s_add_u32 m0, s64, 0xb000
	v_mfma_f32_16x16x32_bf16 v[10:13], v[168:171], v[172:175], v[10:13]
	v_mfma_f32_16x16x32_bf16 v[6:9], v[168:171], v[176:179], v[6:9]
	global_load_lds_dwordx4 v143, s[60:61]
	v_mfma_f32_16x16x32_bf16 v[2:5], v[168:171], v[180:183], v[2:5]
	v_mfma_f32_16x16x32_bf16 v[42:45], v[168:171], v[184:187], v[42:45]
	s_add_u32 s60, s60, 0x80
	s_addc_u32 s61, s61, 0
	s_sub_i32 s65, s65, 1
	s_cmp_lg_u32 s65, 0
	s_cbranch_scc1 .Levwin_loop
	ds_read_b128 v[148:151], v138 offset:0
	ds_read_b128 v[172:175], v139 offset:16384
	ds_read_b128 v[176:179], v139 offset:18432
	ds_read_b128 v[152:155], v138 offset:2048
	ds_read_b128 v[180:183], v139 offset:20480
	ds_read_b128 v[184:187], v139 offset:22528
	ds_read_b128 v[156:159], v138 offset:4096
	ds_read_b128 v[168:171], v138 offset:6144
	s_waitcnt lgkmcnt(8)
	s_add_u32 m0, s64, 0xc000
	v_mfma_f32_16x16x32_bf16 v[62:65], v[66:69], v[82:85], v[62:65]
	v_mfma_f32_16x16x32_bf16 v[58:61], v[66:69], v[86:89], v[58:61]
	global_load_lds_dwordx4 v144, s[62:63]
	v_mfma_f32_16x16x32_bf16 v[54:57], v[66:69], v[90:93], v[54:57]
	v_mfma_f32_16x16x32_bf16 v[50:53], v[66:69], v[94:97], v[50:53]
	s_add_u32 m0, s64, 0xd000
	v_mfma_f32_16x16x32_bf16 v[46:49], v[70:73], v[82:85], v[46:49]
	v_mfma_f32_16x16x32_bf16 v[38:41], v[70:73], v[86:89], v[38:41]
	global_load_lds_dwordx4 v145, s[62:63]
	v_mfma_f32_16x16x32_bf16 v[34:37], v[70:73], v[90:93], v[34:37]
	v_mfma_f32_16x16x32_bf16 v[30:33], v[70:73], v[94:97], v[30:33]
	s_add_u32 m0, s64, 0xe000
	v_mfma_f32_16x16x32_bf16 v[26:29], v[74:77], v[82:85], v[26:29]
	v_mfma_f32_16x16x32_bf16 v[22:25], v[74:77], v[86:89], v[22:25]
	global_load_lds_dwordx4 v146, s[62:63]
	v_mfma_f32_16x16x32_bf16 v[18:21], v[74:77], v[90:93], v[18:21]
	v_mfma_f32_16x16x32_bf16 v[14:17], v[74:77], v[94:97], v[14:17]
	s_add_u32 m0, s64, 0xf000
	v_mfma_f32_16x16x32_bf16 v[10:13], v[78:81], v[82:85], v[10:13]
	v_mfma_f32_16x16x32_bf16 v[6:9], v[78:81], v[86:89], v[6:9]
	global_load_lds_dwordx4 v147, s[62:63]
	v_mfma_f32_16x16x32_bf16 v[2:5], v[78:81], v[90:93], v[2:5]
	v_mfma_f32_16x16x32_bf16 v[42:45], v[78:81], v[94:97], v[42:45]
	s_add_u32 s62, s62, 0x80
	s_addc_u32 s63, s63, 0
	s_waitcnt lgkmcnt(0)
	s_barrier
	v_mfma_f32_16x16x32_bf16 v[62:65], v[148:151], v[172:175], v[62:65]
	v_mfma_f32_16x16x32_bf16 v[58:61], v[148:151], v[176:179], v[58:61]
	v_mfma_f32_16x16x32_bf16 v[54:57], v[148:151], v[180:183], v[54:57]
	v_mfma_f32_16x16x32_bf16 v[50:53], v[148:151], v[184:187], v[50:53]
	v_mfma_f32_16x16x32_bf16 v[46:49], v[152:155], v[172:175], v[46:49]
	v_mfma_f32_16x16x32_bf16 v[38:41], v[152:155], v[176:179], v[38:41]
	v_mfma_f32_16x16x32_bf16 v[34:37], v[152:155], v[180:183], v[34:37]
	v_mfma_f32_16x16x32_bf16 v[30:33], v[152:155], v[184:187], v[30:33]
	s_waitcnt vmcnt(0)
	s_barrier
	ds_read_b128 v[66:69], v136 offset:32768
	ds_read_b128 v[82:85], v137 offset:49152
	ds_read_b128 v[86:89], v137 offset:51200
	ds_read_b128 v[70:73], v136 offset:34816
	ds_read_b128 v[90:93], v137 offset:53248
	ds_read_b128 v[94:97], v137 offset:55296
	ds_read_b128 v[74:77], v136 offset:36864
	ds_read_b128 v[78:81], v136 offset:38912
	v_mfma_f32_16x16x32_bf16 v[26:29], v[156:159], v[172:175], v[26:29]
	v_mfma_f32_16x16x32_bf16 v[22:25], v[156:159], v[176:179], v[22:25]
	v_mfma_f32_16x16x32_bf16 v[18:21], v[156:159], v[180:183], v[18:21]
	v_mfma_f32_16x16x32_bf16 v[14:17], v[156:159], v[184:187], v[14:17]
	v_mfma_f32_16x16x32_bf16 v[10:13], v[168:171], v[172:175], v[10:13]
	v_mfma_f32_16x16x32_bf16 v[6:9], v[168:171], v[176:179], v[6:9]
	v_mfma_f32_16x16x32_bf16 v[2:5], v[168:171], v[180:183], v[2:5]
	v_mfma_f32_16x16x32_bf16 v[42:45], v[168:171], v[184:187], v[42:45]
	ds_read_b128 v[148:151], v138 offset:32768
	ds_read_b128 v[172:175], v139 offset:49152
	ds_read_b128 v[176:179], v139 offset:51200
	ds_read_b128 v[152:155], v138 offset:34816
	ds_read_b128 v[180:183], v139 offset:53248
	ds_read_b128 v[184:187], v139 offset:55296
	ds_read_b128 v[156:159], v138 offset:36864
	ds_read_b128 v[168:171], v138 offset:38912
	s_waitcnt lgkmcnt(8)
	v_mfma_f32_16x16x32_bf16 v[62:65], v[66:69], v[82:85], v[62:65]
	v_mfma_f32_16x16x32_bf16 v[58:61], v[66:69], v[86:89], v[58:61]
	v_mfma_f32_16x16x32_bf16 v[54:57], v[66:69], v[90:93], v[54:57]
	v_mfma_f32_16x16x32_bf16 v[50:53], v[66:69], v[94:97], v[50:53]
	v_mfma_f32_16x16x32_bf16 v[46:49], v[70:73], v[82:85], v[46:49]
	v_mfma_f32_16x16x32_bf16 v[38:41], v[70:73], v[86:89], v[38:41]
	v_mfma_f32_16x16x32_bf16 v[34:37], v[70:73], v[90:93], v[34:37]
	v_mfma_f32_16x16x32_bf16 v[30:33], v[70:73], v[94:97], v[30:33]
	v_mfma_f32_16x16x32_bf16 v[26:29], v[74:77], v[82:85], v[26:29]
	v_mfma_f32_16x16x32_bf16 v[22:25], v[74:77], v[86:89], v[22:25]
	v_mfma_f32_16x16x32_bf16 v[18:21], v[74:77], v[90:93], v[18:21]
	v_mfma_f32_16x16x32_bf16 v[14:17], v[74:77], v[94:97], v[14:17]
	v_mfma_f32_16x16x32_bf16 v[10:13], v[78:81], v[82:85], v[10:13]
	v_mfma_f32_16x16x32_bf16 v[6:9], v[78:81], v[86:89], v[6:9]
	v_mfma_f32_16x16x32_bf16 v[2:5], v[78:81], v[90:93], v[2:5]
	v_mfma_f32_16x16x32_bf16 v[42:45], v[78:81], v[94:97], v[42:45]
	s_waitcnt lgkmcnt(0)
	s_barrier
	v_mfma_f32_16x16x32_bf16 v[62:65], v[148:151], v[172:175], v[62:65]
	v_mfma_f32_16x16x32_bf16 v[58:61], v[148:151], v[176:179], v[58:61]
	v_mfma_f32_16x16x32_bf16 v[54:57], v[148:151], v[180:183], v[54:57]
	v_mfma_f32_16x16x32_bf16 v[50:53], v[148:151], v[184:187], v[50:53]
	v_mfma_f32_16x16x32_bf16 v[46:49], v[152:155], v[172:175], v[46:49]
	v_mfma_f32_16x16x32_bf16 v[38:41], v[152:155], v[176:179], v[38:41]
	v_mfma_f32_16x16x32_bf16 v[34:37], v[152:155], v[180:183], v[34:37]
	v_mfma_f32_16x16x32_bf16 v[30:33], v[152:155], v[184:187], v[30:33]
	v_mfma_f32_16x16x32_bf16 v[26:29], v[156:159], v[172:175], v[26:29]
	v_mfma_f32_16x16x32_bf16 v[22:25], v[156:159], v[176:179], v[22:25]
	v_mfma_f32_16x16x32_bf16 v[18:21], v[156:159], v[180:183], v[18:21]
	v_mfma_f32_16x16x32_bf16 v[14:17], v[156:159], v[184:187], v[14:17]
	v_mfma_f32_16x16x32_bf16 v[10:13], v[168:171], v[172:175], v[10:13]
	v_mfma_f32_16x16x32_bf16 v[6:9], v[168:171], v[176:179], v[6:9]
	v_mfma_f32_16x16x32_bf16 v[2:5], v[168:171], v[180:183], v[2:5]
	v_mfma_f32_16x16x32_bf16 v[42:45], v[168:171], v[184:187], v[42:45]
